# ssq epilogue loads batched (SWIGLU/STORE), P stores nt in phase 4, phase_final loads batched
# baseline (speedup 1.0000x reference)
; #define TIDX opaque_tid()
; #define BIDX opaque_bid()
; #define GDIM opaque_gdim()
; #define AIN(i) ((const float*)(__attribute__((address_space(1))) const float*)karg_u64(8 * (i)))
; __device__ __forceinline__ void phase_final(const Args& a) {
;     const int lane = TIDX & 63, gw = BIDX * 8 + (TIDX >> 6), ngw = GDIM * 8;
;     f32x4 gg[8];
; #pragma unroll
;     for (int j = 0; j < 8; ++j) gg[j] = ((const f32x4*)AIN(24))[lane + 64 * j];
;     for (int r = gw; r < NT; r += ngw) {
;         f32x4* xr = (f32x4*)(AOUT + (size_t)r * DM) + lane;
;         f32x4 v[8]; float s = 0.f;
; #pragma unroll
;         for (int j = 0; j < 8; ++j) { v[j] = __builtin_nontemporal_load(xr + 64 * j); s += v[j].x * v[j].x + v[j].y * v[j].y + v[j].z * v[j].z + v[j].w * v[j].w; }
;         const float rs = rsqrtf(wave_sum(s) * (1.f / DM) + 1e-6f);
; #pragma unroll
;         for (int j = 0; j < 8; ++j) xr[64 * j] = v[j] * rs * gg[j];
;     }
; }
.LBB0_27:
	s_mov_b64 s[20:21], s[0:1]
	s_load_dwordx2 s[20:21], s[20:21], 0xc8
	v_xor_b32_e32 v76, 1, v226
	v_xor_b32_e32 v75, 32, v226
	v_add_u32_e32 v64, s14, v64
	s_waitcnt vmcnt(8) lgkmcnt(0)
	v_lshl_add_u64 v[68:69], s[20:21], 0, v[66:67]
	global_load_dwordx4 v[82:85], v[68:69], off nt
	global_load_dwordx4 v[86:89], v[68:69], off offset:1024 nt
	global_load_dwordx4 v[90:93], v[68:69], off offset:2048 nt
	global_load_dwordx4 v[94:97], v[68:69], off offset:3072 nt
	global_load_dwordx4 v[98:101], v[68:69], off offset:-4096 nt
	global_load_dwordx4 v[102:105], v[68:69], off offset:-3072 nt
	global_load_dwordx4 v[106:109], v[68:69], off offset:-2048 nt
	global_load_dwordx4 v[110:113], v[68:69], off offset:-1024 nt
	s_nop 0
	s_nop 0
	s_nop 0
	s_nop 0
	s_nop 0
	v_lshl_add_u64 v[66:67], v[66:67], 0, s[16:17]
	s_nop 0
	s_waitcnt vmcnt(7)
	v_mov_b32_e32 v54, v83
	s_nop 0
	s_waitcnt vmcnt(6)
	v_mov_b32_e32 v55, v87
	v_mov_b32_e32 v52, v82
	v_mov_b32_e32 v53, v86
	v_pk_mul_f32 v[54:55], v[54:55], v[54:55]
	v_mov_b32_e32 v56, v84
	v_pk_fma_f32 v[52:53], v[52:53], v[52:53], v[54:55]
	s_nop 0
	s_waitcnt vmcnt(5)
	v_mov_b32_e32 v54, v91
	s_nop 0
	s_waitcnt vmcnt(4)
	v_mov_b32_e32 v55, v95
	v_mov_b32_e32 v57, v88
	v_mov_b32_e32 v58, v90
	v_mov_b32_e32 v59, v94
	v_pk_mul_f32 v[54:55], v[54:55], v[54:55]
	v_pk_fma_f32 v[52:53], v[56:57], v[56:57], v[52:53]
	v_pk_fma_f32 v[54:55], v[58:59], v[58:59], v[54:55]
	v_mov_b32_e32 v56, v92
	v_mov_b32_e32 v57, v96
	v_mov_b32_e32 v58, v85
	v_mov_b32_e32 v59, v89
	v_pk_fma_f32 v[54:55], v[56:57], v[56:57], v[54:55]
	v_mov_b32_e32 v56, v93
	v_mov_b32_e32 v57, v97
	v_pk_fma_f32 v[70:71], v[58:59], v[58:59], v[52:53]
	v_pk_fma_f32 v[72:73], v[56:57], v[56:57], v[54:55]
	s_nop 0
	s_nop 0
	s_waitcnt vmcnt(3)
	v_mul_f32_e32 v56, v99, v99
	v_fmac_f32_e32 v56, v98, v98
	v_fmac_f32_e32 v56, v100, v100
	v_fmac_f32_e32 v56, v101, v101
	s_nop 0
	s_waitcnt vmcnt(2)
	v_mul_f32_e32 v57, v103, v103
	v_fmac_f32_e32 v57, v102, v102
	v_fmac_f32_e32 v57, v104, v104
	v_fmac_f32_e32 v57, v105, v105
	v_add_f32_e32 v65, v56, v57
	s_nop 0
	s_nop 0
	s_nop 0
	s_waitcnt vmcnt(1)
	v_mul_f32_e32 v74, v107, v107
	v_fmac_f32_e32 v74, v106, v106
	v_fmac_f32_e32 v74, v108, v108
	v_fmac_f32_e32 v74, v109, v109
	v_add_f32_e32 v65, v65, v74
	s_nop 0
	s_waitcnt vmcnt(0)
	v_mul_f32_e32 v74, v111, v111
	v_fmac_f32_e32 v74, v110, v110
	v_fmac_f32_e32 v74, v112, v112
	v_fmac_f32_e32 v74, v113, v113
	v_add_f32_e32 v65, v65, v74
	v_add_f32_e32 v65, v65, v70
	v_add_f32_e32 v65, v65, v71
	v_and_b32_e32 v70, 64, v226
	v_add_f32_e32 v65, v65, v72
	v_add_u32_e32 v70, 64, v70
	v_add_f32_e32 v65, v65, v73
	v_xor_b32_e32 v71, 2, v226
	v_xor_b32_e32 v72, 4, v226
	v_xor_b32_e32 v73, 8, v226
	v_xor_b32_e32 v74, 16, v226
	v_cmp_lt_i32_e64 s[48:49], v76, v70
	v_cmp_lt_i32_e32 vcc, v71, v70
	v_cmp_lt_i32_e64 s[40:41], v72, v70
	v_cmp_lt_i32_e64 s[42:43], v73, v70
	v_cmp_lt_i32_e64 s[44:45], v74, v70
	v_cmp_lt_i32_e64 s[46:47], v75, v70
	v_cndmask_b32_e64 v70, v226, v76, s[48:49]
	v_lshlrev_b32_e32 v70, 2, v70
	ds_bpermute_b32 v70, v70, v65
	s_waitcnt lgkmcnt(0)
	v_add_f32_e32 v65, v65, v70
	v_cndmask_b32_e32 v70, v226, v71, vcc
	v_lshlrev_b32_e32 v70, 2, v70
	ds_bpermute_b32 v70, v70, v65
	s_waitcnt lgkmcnt(0)
	v_add_f32_e32 v65, v65, v70
	v_cndmask_b32_e64 v70, v226, v72, s[40:41]
	v_lshlrev_b32_e32 v70, 2, v70
	ds_bpermute_b32 v70, v70, v65
	s_waitcnt lgkmcnt(0)
	v_add_f32_e32 v65, v65, v70
	v_cndmask_b32_e64 v70, v226, v73, s[42:43]
	v_lshlrev_b32_e32 v70, 2, v70
	ds_bpermute_b32 v70, v70, v65
	s_waitcnt lgkmcnt(0)
	v_add_f32_e32 v65, v65, v70
	v_cndmask_b32_e64 v70, v226, v74, s[44:45]
	v_lshlrev_b32_e32 v70, 2, v70
	ds_bpermute_b32 v70, v70, v65
	s_waitcnt lgkmcnt(0)
	v_add_f32_e32 v65, v65, v70
	v_cndmask_b32_e64 v70, v226, v75, s[46:47]
	v_lshlrev_b32_e32 v70, 2, v70
	ds_bpermute_b32 v70, v70, v65
	s_waitcnt lgkmcnt(0)
	v_add_f32_e32 v65, v65, v70
	v_fmamk_f32 v65, v65, 0x3a000000, v228
	v_mul_f32_e32 v70, 0x4b800000, v65
	v_cmp_gt_f32_e32 vcc, s96, v65
	s_nop 1
	v_cndmask_b32_e32 v65, v65, v70, vcc
	v_rsq_f32_e32 v65, v65
	s_nop 0
	v_mul_f32_e32 v70, 0x45800000, v65
	v_cndmask_b32_e32 v70, v65, v70, vcc
	v_pk_mul_f32 v[48:49], v[98:99], v[70:71] op_sel_hi:[1,0]
	v_pk_mul_f32 v[50:51], v[100:101], v[70:71] op_sel_hi:[1,0]
	v_pk_mul_f32 v[52:53], v[102:103], v[70:71] op_sel_hi:[1,0]
	v_pk_mul_f32 v[54:55], v[104:105], v[70:71] op_sel_hi:[1,0]
	v_pk_mul_f32 v[60:61], v[106:107], v[70:71] op_sel_hi:[1,0]
	v_pk_mul_f32 v[62:63], v[108:109], v[70:71] op_sel_hi:[1,0]
	v_pk_mul_f32 v[56:57], v[110:111], v[70:71] op_sel_hi:[1,0]
	v_pk_mul_f32 v[58:59], v[112:113], v[70:71] op_sel_hi:[1,0]
	v_pk_mul_f32 v[44:45], v[82:83], v[70:71] op_sel_hi:[1,0]
	v_pk_mul_f32 v[46:47], v[84:85], v[70:71] op_sel_hi:[1,0]
	v_pk_mul_f32 v[72:73], v[86:87], v[70:71] op_sel_hi:[1,0]
	v_pk_mul_f32 v[74:75], v[88:89], v[70:71] op_sel_hi:[1,0]
	v_pk_mul_f32 v[76:77], v[90:91], v[70:71] op_sel_hi:[1,0]
	v_pk_mul_f32 v[78:79], v[92:93], v[70:71] op_sel_hi:[1,0]
	v_pk_mul_f32 v[80:81], v[94:95], v[70:71] op_sel_hi:[1,0]
	v_pk_mul_f32 v[70:71], v[96:97], v[70:71] op_sel_hi:[1,0]
	v_pk_mul_f32 v[34:35], v[2:3], v[50:51]
	v_pk_mul_f32 v[32:33], v[0:1], v[48:49]
	v_cmp_lt_i32_e32 vcc, s67, v64
	global_store_dwordx4 v[68:69], v[32:35], off offset:-4096
	s_or_b64 s[18:19], vcc, s[18:19]
	v_pk_mul_f32 v[38:39], v[10:11], v[62:63]
	v_pk_mul_f32 v[34:35], v[6:7], v[54:55]
	v_pk_mul_f32 v[32:33], v[4:5], v[52:53]
	v_pk_mul_f32 v[36:37], v[8:9], v[60:61]
	v_pk_mul_f32 v[42:43], v[14:15], v[58:59]
	v_pk_mul_f32 v[40:41], v[12:13], v[56:57]
	v_pk_mul_f32 v[46:47], v[18:19], v[46:47]
	v_pk_mul_f32 v[44:45], v[16:17], v[44:45]
	v_pk_mul_f32 v[50:51], v[22:23], v[74:75]
	v_pk_mul_f32 v[48:49], v[20:21], v[72:73]
	v_pk_mul_f32 v[54:55], v[26:27], v[78:79]
	v_pk_mul_f32 v[52:53], v[24:25], v[76:77]
	v_pk_mul_f32 v[58:59], v[30:31], v[70:71]
	v_pk_mul_f32 v[56:57], v[28:29], v[80:81]
	global_store_dwordx4 v[68:69], v[32:35], off offset:-3072
	global_store_dwordx4 v[68:69], v[36:39], off offset:-2048
	global_store_dwordx4 v[68:69], v[40:43], off offset:-1024
	global_store_dwordx4 v[68:69], v[44:47], off
	global_store_dwordx4 v[68:69], v[48:51], off offset:1024
	global_store_dwordx4 v[68:69], v[52:55], off offset:2048
	global_store_dwordx4 v[68:69], v[56:59], off offset:3072
	s_andn2_b64 exec, exec, s[18:19]
	s_cbranch_execnz .LBB0_27

; template <int EPI> ...
;     ...
;         float rs[2][4];
; #pragma unroll
;         for (int ai = 0; ai < 2; ++ai)
; #pragma unroll
;             for (int m = 0; m < 4; ++m) {
;                 const f32x4 q0 = *(const f32x4*)(ssq_in + (size_t)(row0 + ai * HALF + m * 16) * 8), q1 = *(const f32x4*)(ssq_in + (size_t)(row0 + ai * HALF + m * 16) * 8 + 4);
;                 rs[ai][m] = rsqrtf((((q0.x + q0.y) + (q0.z + q0.w)) + ((q1.x + q1.y) + (q1.z + q1.w))) * (1.f / DM) + 1e-6f);
;             }
.LBB0_111:
	s_or_b64 exec, exec, s[20:21]
	v_mov_b32_e32 v137, v224
	v_mov_b64_e32 v[150:151], s[62:63]
	v_ashrrev_i32_e32 v128, 2, v137
	v_and_b32_e32 v128, 0xffffffc0, v128
	v_and_or_b32 v129, v137, 15, s18
	v_add_u32_e32 v148, v129, v128
	v_ashrrev_i32_e32 v149, 31, v148
	v_lshlrev_b64 v[128:129], 5, v[148:149]
	v_lshl_add_u64 v[128:129], s[16:17], 0, v[128:129]
	global_load_dwordx4 v[160:163], v[128:129], off
	global_load_dwordx4 v[164:167], v[128:129], off offset:16
	global_load_dwordx4 v[168:171], v[128:129], off offset:512
	global_load_dwordx4 v[172:175], v[128:129], off offset:528
	global_load_dwordx4 v[176:179], v[128:129], off offset:1024
	global_load_dwordx4 v[180:183], v[128:129], off offset:1040
	global_load_dwordx4 v[184:187], v[128:129], off offset:1536
	global_load_dwordx4 v[188:191], v[128:129], off offset:1552
	v_add_co_u32_e32 v158, vcc, 0x1000, v128
	s_nop 1
	v_addc_co_u32_e32 v159, vcc, 0, v129, vcc
	global_load_dwordx4 v[192:195], v[158:159], off
	global_load_dwordx4 v[196:199], v[158:159], off offset:16
	global_load_dwordx4 v[200:203], v[158:159], off offset:512
	global_load_dwordx4 v[204:207], v[158:159], off offset:528
	global_load_dwordx4 v[208:211], v[158:159], off offset:1024
	global_load_dwordx4 v[216:219], v[158:159], off offset:1040
	global_load_dwordx4 v[220:223], v[158:159], off offset:1536
	global_load_dwordx4 v[238:241], v[158:159], off offset:1552
	s_waitcnt vmcnt(14)
	v_mov_b32_e32 v130, v160
	v_mov_b32_e32 v131, v161
	v_mov_b32_e32 v132, v162
	v_mov_b32_e32 v133, v163
	v_mov_b32_e32 v138, v164
	v_mov_b32_e32 v139, v165
	v_mov_b32_e32 v140, v166
	v_mov_b32_e32 v141, v167
	s_mov_b32 s20, 0x3a000000
	s_mov_b64 s[18:19], 0x1000
	v_and_b32_e32 v214, 0xc0, v137
	v_mov_b32_e32 v134, v130
	v_mov_b32_e32 v135, v138
	v_mov_b32_e32 v138, v131
	v_pk_add_f32 v[130:131], v[134:135], v[138:139]
	v_mov_b32_e32 v134, v132
	v_mov_b32_e32 v135, v140
	v_mov_b32_e32 v140, v133
	v_pk_add_f32 v[132:133], v[134:135], v[140:141]
	s_nop 0
	v_pk_add_f32 v[134:135], v[130:131], v[132:133]
	v_or_b32_e32 v130, 16, v148
	v_ashrrev_i32_e32 v131, 31, v130
	v_lshlrev_b64 v[130:131], 5, v[130:131]
	v_lshl_add_u64 v[138:139], s[16:17], 0, v[130:131]
	s_waitcnt vmcnt(12)
	v_mov_b32_e32 v130, v168
	v_mov_b32_e32 v131, v169
	v_mov_b32_e32 v132, v170
	v_mov_b32_e32 v133, v171
	s_nop 0
	v_mov_b32_e32 v138, v172
	v_mov_b32_e32 v139, v173
	v_mov_b32_e32 v140, v174
	v_mov_b32_e32 v141, v175
	v_mov_b32_e32 v142, v130
	v_mov_b32_e32 v143, v138
	v_mov_b32_e32 v138, v131
	v_pk_add_f32 v[130:131], v[142:143], v[138:139]
	v_mov_b32_e32 v138, v132
	v_mov_b32_e32 v139, v140
	v_mov_b32_e32 v140, v133
	v_pk_add_f32 v[132:133], v[138:139], v[140:141]
	s_nop 0
	v_pk_add_f32 v[130:131], v[130:131], v[132:133]
	v_mov_b32_e32 v133, v134
	v_mov_b32_e32 v132, v130
	v_mov_b32_e32 v134, v131
	v_pk_add_f32 v[130:131], v[132:133], v[134:135]
	s_nop 0
	v_pk_fma_f32 v[130:131], v[130:131], s[20:21], v[150:151] op_sel_hi:[1,0,0]
	s_nop 0
	v_mul_f32_e32 v132, 0x4b800000, v131
	v_cmp_gt_f32_e64 s[40:41], s96, v131
	v_cmp_gt_f32_e32 vcc, s96, v130
	s_nop 0
	v_cndmask_b32_e64 v131, v131, v132, s[40:41]
	v_rsq_f32_e32 v131, v131
	s_nop 0
	v_mul_f32_e32 v132, 0x45800000, v131
	v_cndmask_b32_e64 v146, v131, v132, s[40:41]
	v_mul_f32_e32 v131, 0x4b800000, v130
	v_cndmask_b32_e32 v130, v130, v131, vcc
	v_rsq_f32_e32 v130, v130
	v_pk_mul_f32 v[120:121], v[120:121], v[146:147] op_sel_hi:[1,0]
	v_pk_mul_f32 v[124:125], v[124:125], v[146:147] op_sel_hi:[1,0]
	v_pk_mul_f32 v[122:123], v[122:123], v[146:147] op_sel_hi:[1,0]
	v_mul_f32_e32 v131, 0x45800000, v130
	v_cndmask_b32_e32 v144, v130, v131, vcc
	v_or_b32_e32 v130, 32, v148
	v_ashrrev_i32_e32 v131, 31, v130
	v_lshlrev_b64 v[130:131], 5, v[130:131]
	v_lshl_add_u64 v[134:135], s[16:17], 0, v[130:131]
	s_waitcnt vmcnt(10)
	v_mov_b32_e32 v130, v176
	v_mov_b32_e32 v131, v177
	v_mov_b32_e32 v132, v178
	v_mov_b32_e32 v133, v179
	v_mov_b32_e32 v138, v180
	v_mov_b32_e32 v139, v181
	v_mov_b32_e32 v140, v182
	v_mov_b32_e32 v141, v183
	v_pk_mul_f32 v[126:127], v[126:127], v[146:147] op_sel_hi:[1,0]
	v_pk_mul_f32 v[112:113], v[112:113], v[146:147] op_sel_hi:[1,0]
	v_pk_mul_f32 v[116:117], v[116:117], v[146:147] op_sel_hi:[1,0]
	v_pk_mul_f32 v[114:115], v[114:115], v[146:147] op_sel_hi:[1,0]
	v_pk_mul_f32 v[118:119], v[118:119], v[146:147] op_sel_hi:[1,0]
	v_pk_mul_f32 v[104:105], v[104:105], v[144:145] op_sel_hi:[1,0]
	v_pk_mul_f32 v[108:109], v[108:109], v[144:145] op_sel_hi:[1,0]
	v_pk_mul_f32 v[106:107], v[106:107], v[144:145] op_sel_hi:[1,0]
	v_pk_mul_f32 v[110:111], v[110:111], v[144:145] op_sel_hi:[1,0]
	v_pk_mul_f32 v[96:97], v[96:97], v[144:145] op_sel_hi:[1,0]
	v_pk_mul_f32 v[100:101], v[100:101], v[144:145] op_sel_hi:[1,0]
	v_pk_mul_f32 v[98:99], v[98:99], v[144:145] op_sel_hi:[1,0]
	v_pk_mul_f32 v[102:103], v[102:103], v[144:145] op_sel_hi:[1,0]
	v_mov_b32_e32 v134, v130
	v_mov_b32_e32 v135, v138
	v_mov_b32_e32 v138, v131
	v_pk_add_f32 v[130:131], v[134:135], v[138:139]
	v_mov_b32_e32 v134, v132
	v_mov_b32_e32 v135, v140
	v_mov_b32_e32 v140, v133
	v_pk_add_f32 v[132:133], v[134:135], v[140:141]
	s_nop 0
	v_pk_add_f32 v[134:135], v[130:131], v[132:133]
	v_or_b32_e32 v130, 48, v148
	v_ashrrev_i32_e32 v131, 31, v130
	v_lshlrev_b64 v[130:131], 5, v[130:131]
	v_lshl_add_u64 v[138:139], s[16:17], 0, v[130:131]
	s_waitcnt vmcnt(8)
; template <int EPI> ...
;     ...
;         float rs[2][4];
; #pragma unroll
;         for (int ai = 0; ai < 2; ++ai)
; #pragma unroll
;             for (int m = 0; m < 4; ++m) {
;                 const f32x4 q0 = *(const f32x4*)(ssq_in + (size_t)(row0 + ai * HALF + m * 16) * 8), q1 = *(const f32x4*)(ssq_in + (size_t)(row0 + ai * HALF + m * 16) * 8 + 4);
;                 rs[ai][m] = rsqrtf((((q0.x + q0.y) + (q0.z + q0.w)) + ((q1.x + q1.y) + (q1.z + q1.w))) * (1.f / DM) + 1e-6f);
;             }
;         if (EPI == EPI_SWIGLU) {
;             bf16_t* base = Cb + (size_t)row0 * ldc + (bcol >> 1) + wc * 32 + 4 * fq;
; #pragma unroll
;             for (int ai = 0; ai < 2; ++ai)
; #pragma unroll
;                 for (int m = 0; m < 4; ++m)
; #pragma unroll
;                     for (int n = 0; n < 2; ++n) {
;                         const f32x4 g = acc[ai][0][m][n] * rs[ai][m], u = acc[ai][1][m][n] * rs[ai][m];
	v_mov_b32_e32 v130, v184
	v_mov_b32_e32 v131, v185
	v_mov_b32_e32 v132, v186
	v_mov_b32_e32 v133, v187
	s_nop 0
	v_mov_b32_e32 v138, v188
	v_mov_b32_e32 v139, v189
	v_mov_b32_e32 v140, v190
	v_mov_b32_e32 v141, v191
	v_mov_b32_e32 v142, v130
	v_mov_b32_e32 v143, v138
	v_mov_b32_e32 v138, v131
	v_pk_add_f32 v[130:131], v[142:143], v[138:139]
	v_mov_b32_e32 v138, v132
	v_mov_b32_e32 v139, v140
	v_mov_b32_e32 v140, v133
	v_pk_add_f32 v[132:133], v[138:139], v[140:141]
	v_lshl_add_u64 v[138:139], v[128:129], 0, s[18:19]
	v_pk_add_f32 v[130:131], v[130:131], v[132:133]
	v_mov_b32_e32 v133, v134
	v_mov_b32_e32 v132, v130
	v_mov_b32_e32 v134, v131
	v_pk_add_f32 v[130:131], v[132:133], v[134:135]
	s_mov_b64 s[18:19], 0x1200
	v_pk_fma_f32 v[130:131], v[130:131], s[20:21], v[150:151] op_sel_hi:[1,0,0]
	s_nop 0
	v_mul_f32_e32 v132, 0x4b800000, v131
	v_cmp_gt_f32_e64 s[40:41], s96, v131
	v_cmp_gt_f32_e32 vcc, s96, v130
	s_nop 0
	v_cndmask_b32_e64 v131, v131, v132, s[40:41]
	v_rsq_f32_e32 v131, v131
	s_nop 0
	v_mul_f32_e32 v132, 0x45800000, v131
	v_cndmask_b32_e64 v142, v131, v132, s[40:41]
	v_mul_f32_e32 v131, 0x4b800000, v130
	v_cndmask_b32_e32 v130, v130, v131, vcc
	v_rsq_f32_e32 v130, v130
	v_pk_mul_f32 v[88:89], v[88:89], v[142:143] op_sel_hi:[1,0]
	v_pk_mul_f32 v[92:93], v[92:93], v[142:143] op_sel_hi:[1,0]
	v_pk_mul_f32 v[90:91], v[90:91], v[142:143] op_sel_hi:[1,0]
	v_mul_f32_e32 v131, 0x45800000, v130
	v_cndmask_b32_e32 v140, v130, v131, vcc
	v_add_co_u32_e32 v130, vcc, s70, v128
	v_pk_mul_f32 v[94:95], v[94:95], v[142:143] op_sel_hi:[1,0]
	s_nop 0
	v_addc_co_u32_e32 v131, vcc, 0, v129, vcc
	s_waitcnt vmcnt(6)
	v_mov_b32_e32 v132, v192
	v_mov_b32_e32 v133, v193
	v_mov_b32_e32 v134, v194
	v_mov_b32_e32 v135, v195
	v_mov_b32_e32 v152, v196
	v_mov_b32_e32 v153, v197
	v_mov_b32_e32 v154, v198
	v_mov_b32_e32 v155, v199
	v_pk_mul_f32 v[80:81], v[80:81], v[142:143] op_sel_hi:[1,0]
	v_pk_mul_f32 v[84:85], v[84:85], v[142:143] op_sel_hi:[1,0]
	v_pk_mul_f32 v[82:83], v[82:83], v[142:143] op_sel_hi:[1,0]
	v_pk_mul_f32 v[86:87], v[86:87], v[142:143] op_sel_hi:[1,0]
	v_pk_mul_f32 v[72:73], v[72:73], v[140:141] op_sel_hi:[1,0]
	v_pk_mul_f32 v[76:77], v[76:77], v[140:141] op_sel_hi:[1,0]
	v_pk_mul_f32 v[74:75], v[74:75], v[140:141] op_sel_hi:[1,0]
	v_pk_mul_f32 v[78:79], v[78:79], v[140:141] op_sel_hi:[1,0]
	v_pk_mul_f32 v[64:65], v[64:65], v[140:141] op_sel_hi:[1,0]
	v_pk_mul_f32 v[68:69], v[68:69], v[140:141] op_sel_hi:[1,0]
	v_pk_mul_f32 v[66:67], v[66:67], v[140:141] op_sel_hi:[1,0]
	v_pk_mul_f32 v[70:71], v[70:71], v[140:141] op_sel_hi:[1,0]
	v_mov_b32_e32 v138, v132
	v_mov_b32_e32 v139, v152
	v_mov_b32_e32 v152, v133
	v_pk_add_f32 v[132:133], v[138:139], v[152:153]
	v_mov_b32_e32 v138, v134
	v_mov_b32_e32 v139, v154
	v_mov_b32_e32 v154, v135
	v_pk_add_f32 v[134:135], v[138:139], v[154:155]
	v_lshl_add_u64 v[152:153], v[128:129], 0, s[18:19]
	v_pk_add_f32 v[138:139], v[132:133], v[134:135]
	s_waitcnt vmcnt(4)
	v_mov_b32_e32 v132, v200
	v_mov_b32_e32 v133, v201
	v_mov_b32_e32 v134, v202
	v_mov_b32_e32 v135, v203
	s_nop 0
	v_mov_b32_e32 v152, v204
	v_mov_b32_e32 v153, v205
	v_mov_b32_e32 v154, v206
	v_mov_b32_e32 v155, v207
	s_mov_b64 s[18:19], 0x1400
	v_mov_b32_e32 v156, v132
	v_mov_b32_e32 v157, v152
	v_mov_b32_e32 v152, v133
	v_pk_add_f32 v[132:133], v[156:157], v[152:153]
	v_mov_b32_e32 v152, v134
	v_mov_b32_e32 v153, v154
	v_mov_b32_e32 v154, v135
	v_pk_add_f32 v[134:135], v[152:153], v[154:155]
	v_lshl_add_u64 v[152:153], v[128:129], 0, s[18:19]
	v_pk_add_f32 v[132:133], v[132:133], v[134:135]
	v_mov_b32_e32 v135, v138
	v_mov_b32_e32 v134, v132
	v_mov_b32_e32 v138, v133
	v_pk_add_f32 v[132:133], v[134:135], v[138:139]
	s_mov_b64 s[18:19], 0x1600
	v_pk_fma_f32 v[132:133], v[132:133], s[20:21], v[150:151] op_sel_hi:[1,0,0]
	s_nop 0
	v_mul_f32_e32 v134, 0x4b800000, v133
	v_cmp_gt_f32_e64 s[40:41], s96, v133
	v_cmp_gt_f32_e32 vcc, s96, v132
	s_nop 0
	v_cndmask_b32_e64 v133, v133, v134, s[40:41]
	v_rsq_f32_e32 v133, v133
	s_nop 0
	v_mul_f32_e32 v134, 0x45800000, v133
	v_cndmask_b32_e64 v138, v133, v134, s[40:41]
	v_mul_f32_e32 v133, 0x4b800000, v132
	v_cndmask_b32_e32 v132, v132, v133, vcc
	v_rsq_f32_e32 v132, v132
	v_pk_mul_f32 v[56:57], v[56:57], v[138:139] op_sel_hi:[1,0]
	v_pk_mul_f32 v[60:61], v[60:61], v[138:139] op_sel_hi:[1,0]
	v_pk_mul_f32 v[58:59], v[58:59], v[138:139] op_sel_hi:[1,0]
	v_mul_f32_e32 v133, 0x45800000, v132
	v_cndmask_b32_e32 v136, v132, v133, vcc
	s_waitcnt vmcnt(2)
	v_mov_b32_e32 v132, v208
	v_mov_b32_e32 v133, v209
	v_mov_b32_e32 v134, v210
	v_mov_b32_e32 v135, v211
	s_nop 0
	v_mov_b32_e32 v152, v216
	v_mov_b32_e32 v153, v217
	v_mov_b32_e32 v154, v218
	v_mov_b32_e32 v155, v219
	v_pk_mul_f32 v[62:63], v[62:63], v[138:139] op_sel_hi:[1,0]
	v_pk_mul_f32 v[48:49], v[48:49], v[138:139] op_sel_hi:[1,0]
	v_pk_mul_f32 v[52:53], v[52:53], v[138:139] op_sel_hi:[1,0]
	v_pk_mul_f32 v[50:51], v[50:51], v[138:139] op_sel_hi:[1,0]
	v_pk_mul_f32 v[54:55], v[54:55], v[138:139] op_sel_hi:[1,0]
	v_pk_mul_f32 v[40:41], v[40:41], v[136:137] op_sel_hi:[1,0]
	v_pk_mul_f32 v[44:45], v[44:45], v[136:137] op_sel_hi:[1,0]
	v_pk_mul_f32 v[42:43], v[42:43], v[136:137] op_sel_hi:[1,0]
	v_pk_mul_f32 v[46:47], v[46:47], v[136:137] op_sel_hi:[1,0]
	v_pk_mul_f32 v[32:33], v[32:33], v[136:137] op_sel_hi:[1,0]
	v_pk_mul_f32 v[36:37], v[36:37], v[136:137] op_sel_hi:[1,0]
	v_pk_mul_f32 v[34:35], v[34:35], v[136:137] op_sel_hi:[1,0]
	v_pk_mul_f32 v[38:39], v[38:39], v[136:137] op_sel_hi:[1,0]
	v_mov_b32_e32 v156, v132
	v_mov_b32_e32 v157, v152
	v_mov_b32_e32 v152, v133
	v_pk_add_f32 v[132:133], v[156:157], v[152:153]
	v_mov_b32_e32 v152, v134
	v_mov_b32_e32 v153, v154
	v_mov_b32_e32 v154, v135
	v_pk_add_f32 v[134:135], v[152:153], v[154:155]
	s_nop 0
	v_pk_add_f32 v[152:153], v[132:133], v[134:135]
	v_lshl_add_u64 v[132:133], v[128:129], 0, s[18:19]
	s_waitcnt vmcnt(0)
; __device__ __forceinline__ unsigned pk2(float lo, float hi) { f32x2_t v = {lo, hi}; bf16x2_t b = __builtin_convertvector(v, bf16x2_t); return __builtin_bit_cast(unsigned, b); }
; __device__ __forceinline__ float siluf_(float x) { return x * __builtin_amdgcn_rcpf(1.f + __expf(-x)); }
; template <int EPI> ...
;     ...
;                 const f32x4 q0 = *(const f32x4*)(ssq_in + (size_t)(row0 + ai * HALF + m * 16) * 8), q1 = *(const f32x4*)(ssq_in + (size_t)(row0 + ai * HALF + m * 16) * 8 + 4);
;                 rs[ai][m] = rsqrtf((((q0.x + q0.y) + (q0.z + q0.w)) + ((q1.x + q1.y) + (q1.z + q1.w))) * (1.f / DM) + 1e-6f);
;             }
;         if (EPI == EPI_SWIGLU) {
;             bf16_t* base = Cb + (size_t)row0 * ldc + (bcol >> 1) + wc * 32 + 4 * fq;
; #pragma unroll
;             for (int ai = 0; ai < 2; ++ai)
; #pragma unroll
;                 for (int m = 0; m < 4; ++m)
; #pragma unroll
;                     for (int n = 0; n < 2; ++n) {
;                         const f32x4 g = acc[ai][0][m][n] * rs[ai][m], u = acc[ai][1][m][n] * rs[ai][m];
;                         u32x2 o; o.x = pk2(siluf_(g.x) * u.x, siluf_(g.y) * u.y); o.y = pk2(siluf_(g.z) * u.z, siluf_(g.w) * u.w);
;                         *(u32x2*)(base + (size_t)(ai * HALF + m * 16) * ldc + n * 16) = o;
;                     }
	v_mov_b32_e32 v128, v220
	v_mov_b32_e32 v129, v221
	v_mov_b32_e32 v130, v222
	v_mov_b32_e32 v131, v223
	s_nop 0
	v_mov_b32_e32 v132, v238
	v_mov_b32_e32 v133, v239
	v_mov_b32_e32 v134, v240
	v_mov_b32_e32 v135, v241
	s_movk_i32 s18, 0x2c00
	v_mov_b32_e32 v154, v128
	v_mov_b32_e32 v155, v132
	v_mov_b32_e32 v132, v129
	v_pk_add_f32 v[128:129], v[154:155], v[132:133]
	v_mov_b32_e32 v132, v130
	v_mov_b32_e32 v133, v134
	v_mov_b32_e32 v134, v131
	v_pk_add_f32 v[130:131], v[132:133], v[134:135]
	s_nop 0
	v_pk_add_f32 v[128:129], v[128:129], v[130:131]
	v_mov_b32_e32 v131, v152
	v_mov_b32_e32 v130, v128
	v_mov_b32_e32 v152, v129
	v_pk_add_f32 v[128:129], v[130:131], v[152:153]
	s_nop 0
	v_pk_fma_f32 v[128:129], v[128:129], s[20:21], v[150:151] op_sel_hi:[1,0,0]
	s_nop 0
	v_mul_f32_e32 v130, 0x4b800000, v129
	v_cmp_gt_f32_e64 s[40:41], s96, v129
	v_cmp_gt_f32_e32 vcc, s96, v128
	s_nop 0
	v_cndmask_b32_e64 v129, v129, v130, s[40:41]
	v_rsq_f32_e32 v129, v129
	s_nop 0
	v_mul_f32_e32 v130, 0x45800000, v129
	v_cndmask_b32_e64 v132, v129, v130, s[40:41]
	v_mul_f32_e32 v129, 0x4b800000, v128
	v_cndmask_b32_e32 v128, v128, v129, vcc
	v_rsq_f32_e32 v128, v128
	v_mov_b64_e32 v[130:131], s[2:3]
	v_mad_i64_i32 v[130:131], s[18:19], v148, s18, v[130:131]
	s_lshl_b32 s18, s38, 7
	v_mul_f32_e32 v129, 0x45800000, v128
	s_ashr_i32 s19, s18, 31
	v_cndmask_b32_e32 v128, v128, v129, vcc
	v_lshl_add_u64 v[130:131], s[18:19], 1, v[130:131]
	v_lshrrev_b32_e32 v129, 1, v137
	v_lshl_add_u64 v[130:131], v[130:131], 0, v[214:215]
	v_and_b32_e32 v214, 24, v129
	v_mul_f32_e32 v129, 0xbfb8aa3b, v120
	v_exp_f32_e32 v129, v129
	v_lshl_add_u64 v[130:131], v[130:131], 0, v[214:215]
	s_mov_b32 s18, 0x2c000
	v_pk_mul_f32 v[24:25], v[24:25], v[132:133] op_sel_hi:[1,0]
	v_add_f32_e32 v129, 1.0, v129
	v_rcp_f32_e32 v134, v129
	v_mul_f32_e32 v129, 0xbfb8aa3b, v121
	v_exp_f32_e32 v129, v129
	v_pk_mul_f32 v[28:29], v[28:29], v[132:133] op_sel_hi:[1,0]
	v_pk_mul_f32 v[26:27], v[26:27], v[132:133] op_sel_hi:[1,0]
	v_pk_mul_f32 v[30:31], v[30:31], v[132:133] op_sel_hi:[1,0]
	v_add_f32_e32 v129, 1.0, v129
	v_rcp_f32_e32 v135, v129
	v_pk_mul_f32 v[16:17], v[16:17], v[132:133] op_sel_hi:[1,0]
	v_pk_mul_f32 v[20:21], v[20:21], v[132:133] op_sel_hi:[1,0]
	v_pk_mul_f32 v[18:19], v[18:19], v[132:133] op_sel_hi:[1,0]
	v_pk_mul_f32 v[120:121], v[120:121], v[134:135]
	v_pk_mul_f32 v[22:23], v[22:23], v[132:133] op_sel_hi:[1,0]
	v_pk_mul_f32 v[120:121], v[124:125], v[120:121]
	v_pk_mul_f32 v[8:9], v[8:9], v[128:129] op_sel_hi:[1,0]
	v_cvt_pk_bf16_f32 v120, v120, v121
	v_mul_f32_e32 v121, 0xbfb8aa3b, v122
	v_exp_f32_e32 v121, v121
	v_pk_mul_f32 v[12:13], v[12:13], v[128:129] op_sel_hi:[1,0]
	v_pk_mul_f32 v[10:11], v[10:11], v[128:129] op_sel_hi:[1,0]
	v_pk_mul_f32 v[14:15], v[14:15], v[128:129] op_sel_hi:[1,0]
	v_add_f32_e32 v121, 1.0, v121
	v_rcp_f32_e32 v124, v121
	v_mul_f32_e32 v121, 0xbfb8aa3b, v123
	v_exp_f32_e32 v121, v121
	v_pk_mul_f32 v[0:1], v[0:1], v[128:129] op_sel_hi:[1,0]
	v_pk_mul_f32 v[4:5], v[4:5], v[128:129] op_sel_hi:[1,0]
	v_pk_mul_f32 v[2:3], v[2:3], v[128:129] op_sel_hi:[1,0]
	v_add_f32_e32 v121, 1.0, v121
	v_rcp_f32_e32 v125, v121
	v_pk_mul_f32 v[6:7], v[6:7], v[128:129] op_sel_hi:[1,0]
	v_pk_mul_f32 v[122:123], v[122:123], v[124:125]
	s_nop 0
	v_pk_mul_f32 v[122:123], v[126:127], v[122:123]
	s_nop 0
	v_cvt_pk_bf16_f32 v121, v122, v123
	global_store_dwordx2 v[130:131], v[120:121], off
	v_mul_f32_e32 v120, 0xbfb8aa3b, v112
	v_mul_f32_e32 v121, 0xbfb8aa3b, v113
	v_exp_f32_e32 v120, v120
	v_exp_f32_e32 v121, v121
	v_add_f32_e32 v120, 1.0, v120
	v_add_f32_e32 v121, 1.0, v121
	v_rcp_f32_e32 v120, v120
	v_rcp_f32_e32 v121, v121
	s_nop 0
	v_pk_mul_f32 v[112:113], v[112:113], v[120:121]
	s_nop 0
	v_pk_mul_f32 v[112:113], v[116:117], v[112:113]
	s_nop 0
	v_cvt_pk_bf16_f32 v112, v112, v113
	v_mul_f32_e32 v113, 0xbfb8aa3b, v114
	v_exp_f32_e32 v113, v113
	s_nop 0
	v_add_f32_e32 v113, 1.0, v113
	v_rcp_f32_e32 v116, v113
	v_mul_f32_e32 v113, 0xbfb8aa3b, v115
	v_exp_f32_e32 v113, v113
	s_nop 0
	v_add_f32_e32 v113, 1.0, v113
	v_rcp_f32_e32 v117, v113
	s_nop 0
	v_pk_mul_f32 v[114:115], v[114:115], v[116:117]
	s_nop 0
	v_pk_mul_f32 v[114:115], v[118:119], v[114:115]
	s_nop 0
	v_cvt_pk_bf16_f32 v113, v114, v115
	global_store_dwordx2 v[130:131], v[112:113], off offset:32
	v_mul_f32_e32 v112, 0xbfb8aa3b, v104
	v_mul_f32_e32 v113, 0xbfb8aa3b, v105
	v_exp_f32_e32 v112, v112
	v_exp_f32_e32 v113, v113
	v_add_f32_e32 v112, 1.0, v112
	v_add_f32_e32 v113, 1.0, v113
	v_rcp_f32_e32 v112, v112
	v_rcp_f32_e32 v113, v113
	s_nop 0
	v_pk_mul_f32 v[104:105], v[104:105], v[112:113]
	s_nop 0
	v_pk_mul_f32 v[104:105], v[108:109], v[104:105]
	s_nop 0
	v_cvt_pk_bf16_f32 v104, v104, v105
	v_mul_f32_e32 v105, 0xbfb8aa3b, v106
	v_exp_f32_e32 v105, v105
	s_nop 0
	v_add_f32_e32 v105, 1.0, v105
	v_rcp_f32_e32 v108, v105
	v_mul_f32_e32 v105, 0xbfb8aa3b, v107
	v_exp_f32_e32 v105, v105
	s_nop 0
	v_add_f32_e32 v105, 1.0, v105
	v_rcp_f32_e32 v109, v105
	s_nop 0
	v_pk_mul_f32 v[106:107], v[106:107], v[108:109]
	s_nop 0
	v_pk_mul_f32 v[106:107], v[110:111], v[106:107]
	s_nop 0
	v_cvt_pk_bf16_f32 v105, v106, v107
	v_add_co_u32_e32 v106, vcc, s18, v130
	s_mov_b32 s18, 0x58000
	s_nop 0
	v_addc_co_u32_e32 v107, vcc, 0, v131, vcc
	global_store_dwordx2 v[106:107], v[104:105], off
	v_mul_f32_e32 v104, 0xbfb8aa3b, v96
	v_mul_f32_e32 v105, 0xbfb8aa3b, v97
	v_exp_f32_e32 v104, v104
	v_exp_f32_e32 v105, v105
	v_add_f32_e32 v104, 1.0, v104
	v_add_f32_e32 v105, 1.0, v105
	v_rcp_f32_e32 v104, v104
	v_rcp_f32_e32 v105, v105
	s_nop 0
	v_pk_mul_f32 v[96:97], v[96:97], v[104:105]
	s_nop 0
	v_pk_mul_f32 v[96:97], v[100:101], v[96:97]
	s_nop 0
; __device__ __forceinline__ unsigned pk2(float lo, float hi) { f32x2_t v = {lo, hi}; bf16x2_t b = __builtin_convertvector(v, bf16x2_t); return __builtin_bit_cast(unsigned, b); }
; __device__ __forceinline__ float siluf_(float x) { return x * __builtin_amdgcn_rcpf(1.f + __expf(-x)); }
; template <int EPI> ...
;     ...
;             bf16_t* base = Cb + (size_t)row0 * ldc + (bcol >> 1) + wc * 32 + 4 * fq;
; #pragma unroll
;             for (int ai = 0; ai < 2; ++ai)
; #pragma unroll
;                 for (int m = 0; m < 4; ++m)
; #pragma unroll
;                     for (int n = 0; n < 2; ++n) {
;                         const f32x4 g = acc[ai][0][m][n] * rs[ai][m], u = acc[ai][1][m][n] * rs[ai][m];
;                         u32x2 o; o.x = pk2(siluf_(g.x) * u.x, siluf_(g.y) * u.y); o.y = pk2(siluf_(g.z) * u.z, siluf_(g.w) * u.w);
;                         *(u32x2*)(base + (size_t)(ai * HALF + m * 16) * ldc + n * 16) = o;
;                     }
	v_cvt_pk_bf16_f32 v96, v96, v97
	v_mul_f32_e32 v97, 0xbfb8aa3b, v98
	v_exp_f32_e32 v97, v97
	s_nop 0
	v_add_f32_e32 v97, 1.0, v97
	v_rcp_f32_e32 v100, v97
	v_mul_f32_e32 v97, 0xbfb8aa3b, v99
	v_exp_f32_e32 v97, v97
	s_nop 0
	v_add_f32_e32 v97, 1.0, v97
	v_rcp_f32_e32 v101, v97
	s_nop 0
	v_pk_mul_f32 v[98:99], v[98:99], v[100:101]
	s_nop 0
	v_pk_mul_f32 v[98:99], v[102:103], v[98:99]
	s_nop 0
	v_cvt_pk_bf16_f32 v97, v98, v99
	global_store_dwordx2 v[106:107], v[96:97], off offset:32
	v_mul_f32_e32 v96, 0xbfb8aa3b, v88
	v_mul_f32_e32 v97, 0xbfb8aa3b, v89
	v_exp_f32_e32 v96, v96
	v_exp_f32_e32 v97, v97
	v_add_f32_e32 v96, 1.0, v96
	v_add_f32_e32 v97, 1.0, v97
	v_rcp_f32_e32 v96, v96
	v_rcp_f32_e32 v97, v97
	s_nop 0
	v_pk_mul_f32 v[88:89], v[88:89], v[96:97]
	s_nop 0
	v_pk_mul_f32 v[88:89], v[92:93], v[88:89]
	s_nop 0
	v_cvt_pk_bf16_f32 v88, v88, v89
	v_mul_f32_e32 v89, 0xbfb8aa3b, v90
	v_exp_f32_e32 v89, v89
	s_nop 0
	v_add_f32_e32 v89, 1.0, v89
	v_rcp_f32_e32 v92, v89
	v_mul_f32_e32 v89, 0xbfb8aa3b, v91
	v_exp_f32_e32 v89, v89
	s_nop 0
	v_add_f32_e32 v89, 1.0, v89
	v_rcp_f32_e32 v93, v89
	s_nop 0
	v_pk_mul_f32 v[90:91], v[90:91], v[92:93]
	s_nop 0
	v_pk_mul_f32 v[90:91], v[94:95], v[90:91]
	s_nop 0
	v_cvt_pk_bf16_f32 v89, v90, v91
	v_add_co_u32_e32 v90, vcc, s18, v130
	s_mov_b32 s18, 0x84000
	s_nop 0
	v_addc_co_u32_e32 v91, vcc, 0, v131, vcc
	global_store_dwordx2 v[90:91], v[88:89], off
	v_mul_f32_e32 v88, 0xbfb8aa3b, v80
	v_mul_f32_e32 v89, 0xbfb8aa3b, v81
	v_exp_f32_e32 v88, v88
	v_exp_f32_e32 v89, v89
	v_add_f32_e32 v88, 1.0, v88
	v_add_f32_e32 v89, 1.0, v89
	v_rcp_f32_e32 v88, v88
	v_rcp_f32_e32 v89, v89
	s_nop 0
	v_pk_mul_f32 v[80:81], v[80:81], v[88:89]
	s_nop 0
	v_pk_mul_f32 v[80:81], v[84:85], v[80:81]
	s_nop 0
	v_cvt_pk_bf16_f32 v80, v80, v81
	v_mul_f32_e32 v81, 0xbfb8aa3b, v82
	v_exp_f32_e32 v81, v81
	s_nop 0
	v_add_f32_e32 v81, 1.0, v81
	v_rcp_f32_e32 v84, v81
	v_mul_f32_e32 v81, 0xbfb8aa3b, v83
	v_exp_f32_e32 v81, v81
	s_nop 0
	v_add_f32_e32 v81, 1.0, v81
	v_rcp_f32_e32 v85, v81
	s_nop 0
	v_pk_mul_f32 v[82:83], v[82:83], v[84:85]
	s_nop 0
	v_pk_mul_f32 v[82:83], v[86:87], v[82:83]
	s_nop 0
	v_cvt_pk_bf16_f32 v81, v82, v83
	global_store_dwordx2 v[90:91], v[80:81], off offset:32
	v_mul_f32_e32 v80, 0xbfb8aa3b, v72
	v_mul_f32_e32 v81, 0xbfb8aa3b, v73
	v_exp_f32_e32 v80, v80
	v_exp_f32_e32 v81, v81
	v_add_f32_e32 v80, 1.0, v80
	v_add_f32_e32 v81, 1.0, v81
	v_rcp_f32_e32 v80, v80
	v_rcp_f32_e32 v81, v81
	s_nop 0
	v_pk_mul_f32 v[72:73], v[72:73], v[80:81]
	s_nop 0
	v_pk_mul_f32 v[72:73], v[76:77], v[72:73]
	s_nop 0
	v_cvt_pk_bf16_f32 v72, v72, v73
	v_mul_f32_e32 v73, 0xbfb8aa3b, v74
	v_exp_f32_e32 v73, v73
	s_nop 0
	v_add_f32_e32 v73, 1.0, v73
	v_rcp_f32_e32 v76, v73
	v_mul_f32_e32 v73, 0xbfb8aa3b, v75
	v_exp_f32_e32 v73, v73
	s_nop 0
	v_add_f32_e32 v73, 1.0, v73
	v_rcp_f32_e32 v77, v73
	s_nop 0
	v_pk_mul_f32 v[74:75], v[74:75], v[76:77]
	s_nop 0
	v_pk_mul_f32 v[74:75], v[78:79], v[74:75]
	s_nop 0
	v_cvt_pk_bf16_f32 v73, v74, v75
	v_add_co_u32_e32 v74, vcc, s18, v130
	s_mov_b32 s18, 0x160000
	s_nop 0
	v_addc_co_u32_e32 v75, vcc, 0, v131, vcc
	global_store_dwordx2 v[74:75], v[72:73], off
	v_mul_f32_e32 v72, 0xbfb8aa3b, v64
	v_mul_f32_e32 v73, 0xbfb8aa3b, v65
	v_exp_f32_e32 v72, v72
	v_exp_f32_e32 v73, v73
	v_add_f32_e32 v72, 1.0, v72
	v_add_f32_e32 v73, 1.0, v73
	v_rcp_f32_e32 v72, v72
	v_rcp_f32_e32 v73, v73
	s_nop 0
	v_pk_mul_f32 v[64:65], v[64:65], v[72:73]
	s_nop 0
	v_pk_mul_f32 v[64:65], v[68:69], v[64:65]
	s_nop 0
	v_cvt_pk_bf16_f32 v64, v64, v65
	v_mul_f32_e32 v65, 0xbfb8aa3b, v66
	v_exp_f32_e32 v65, v65
	s_nop 0
	v_add_f32_e32 v65, 1.0, v65
	v_rcp_f32_e32 v68, v65
	v_mul_f32_e32 v65, 0xbfb8aa3b, v67
	v_exp_f32_e32 v65, v65
	s_nop 0
	v_add_f32_e32 v65, 1.0, v65
	v_rcp_f32_e32 v69, v65
	s_nop 0
	v_pk_mul_f32 v[66:67], v[66:67], v[68:69]
	s_nop 0
	v_pk_mul_f32 v[66:67], v[70:71], v[66:67]
	s_nop 0
	v_cvt_pk_bf16_f32 v65, v66, v67
	global_store_dwordx2 v[74:75], v[64:65], off offset:32
	v_mul_f32_e32 v64, 0xbfb8aa3b, v56
	v_mul_f32_e32 v65, 0xbfb8aa3b, v57
	v_exp_f32_e32 v64, v64
	v_exp_f32_e32 v65, v65
	v_add_f32_e32 v64, 1.0, v64
	v_add_f32_e32 v65, 1.0, v65
	v_rcp_f32_e32 v64, v64
	v_rcp_f32_e32 v65, v65
	s_nop 0
	v_pk_mul_f32 v[56:57], v[56:57], v[64:65]
	s_nop 0
	v_pk_mul_f32 v[56:57], v[60:61], v[56:57]
	s_nop 0
	v_cvt_pk_bf16_f32 v56, v56, v57
	v_mul_f32_e32 v57, 0xbfb8aa3b, v58
	v_exp_f32_e32 v57, v57
	s_nop 0
	v_add_f32_e32 v57, 1.0, v57
	v_rcp_f32_e32 v60, v57
	v_mul_f32_e32 v57, 0xbfb8aa3b, v59
	v_exp_f32_e32 v57, v57
	s_nop 0
	v_add_f32_e32 v57, 1.0, v57
	v_rcp_f32_e32 v61, v57
	s_nop 0
	v_pk_mul_f32 v[58:59], v[58:59], v[60:61]
	s_nop 0
	v_pk_mul_f32 v[58:59], v[62:63], v[58:59]
	s_nop 0
	v_cvt_pk_bf16_f32 v57, v58, v59
	v_add_co_u32_e32 v58, vcc, s18, v130
	s_mov_b32 s18, 0x18c000
	s_nop 0
	v_addc_co_u32_e32 v59, vcc, 0, v131, vcc
	global_store_dwordx2 v[58:59], v[56:57], off
	v_mul_f32_e32 v56, 0xbfb8aa3b, v48
	v_mul_f32_e32 v57, 0xbfb8aa3b, v49
	v_exp_f32_e32 v56, v56
	v_exp_f32_e32 v57, v57
	v_add_f32_e32 v56, 1.0, v56
	v_add_f32_e32 v57, 1.0, v57
	v_rcp_f32_e32 v56, v56
	v_rcp_f32_e32 v57, v57
	s_nop 0
	v_pk_mul_f32 v[48:49], v[48:49], v[56:57]
	s_nop 0
	v_pk_mul_f32 v[48:49], v[52:53], v[48:49]
	s_nop 0
	v_cvt_pk_bf16_f32 v48, v48, v49
	v_mul_f32_e32 v49, 0xbfb8aa3b, v50
	v_exp_f32_e32 v49, v49
	s_nop 0
	v_add_f32_e32 v49, 1.0, v49
	v_rcp_f32_e32 v52, v49
	v_mul_f32_e32 v49, 0xbfb8aa3b, v51
	v_exp_f32_e32 v49, v49
	s_nop 0
; #define BIDX opaque_bid()
; #define GDIM opaque_gdim()
; __device__ __forceinline__ unsigned pk2(float lo, float hi) { f32x2_t v = {lo, hi}; bf16x2_t b = __builtin_convertvector(v, bf16x2_t); return __builtin_bit_cast(unsigned, b); }
; __device__ __forceinline__ float siluf_(float x) { return x * __builtin_amdgcn_rcpf(1.f + __expf(-x)); }
; template <int EPI> ...
;     ...
;             for (int ai = 0; ai < 2; ++ai)
; #pragma unroll
;                 for (int m = 0; m < 4; ++m)
; #pragma unroll
;                     for (int n = 0; n < 2; ++n) {
;                         const f32x4 g = acc[ai][0][m][n] * rs[ai][m], u = acc[ai][1][m][n] * rs[ai][m];
;                         u32x2 o; o.x = pk2(siluf_(g.x) * u.x, siluf_(g.y) * u.y); o.y = pk2(siluf_(g.z) * u.z, siluf_(g.w) * u.w);
;                         *(u32x2*)(base + (size_t)(ai * HALF + m * 16) * ldc + n * 16) = o;
;                     }
; template <int EPI>
; __device__ __forceinline__ void gemm_phase(const bf16_t* A, const bf16_t* Bt, int M, int N, int K, bf16_t* shm,
;                                            float* Cf, bf16_t* Cb, int ldc, float scale, const float* gvec, bf16_t* XNout, float* ssq_out, const float* ssq_in) {
;     ...
;     for (int L = BIDX; L < nwg; L += GDIM) {
;         int wgid = L;
;         { int q = nwg / NXCD, r = nwg % NXCD, xcd = wgid % NXCD, off = wgid / NXCD;
;           wgid = (xcd < r ? xcd * (q + 1) : r * (q + 1) + (xcd - r) * q) + off; }
;         int nig = WGM * nN, gid = wgid / nig, fm = gid * WGM, gsz = min(nM - fm, WGM);
;         int pm = fm + ((wgid % nig) % gsz), pn = (wgid % nig) / gsz;
;         gemm_unit<EPI>(A, Bt, K, pm * BM, pn * BM, shm, Cf, Cb, ldc, scale, gvec, XNout, ssq_out, ssq_in);
;     }
	v_add_f32_e32 v49, 1.0, v49
	v_rcp_f32_e32 v53, v49
	s_nop 0
	v_pk_mul_f32 v[50:51], v[50:51], v[52:53]
	s_nop 0
	v_pk_mul_f32 v[50:51], v[54:55], v[50:51]
	s_nop 0
	v_cvt_pk_bf16_f32 v49, v50, v51
	global_store_dwordx2 v[58:59], v[48:49], off offset:32
	v_mul_f32_e32 v48, 0xbfb8aa3b, v40
	v_mul_f32_e32 v49, 0xbfb8aa3b, v41
	v_exp_f32_e32 v48, v48
	v_exp_f32_e32 v49, v49
	v_add_f32_e32 v48, 1.0, v48
	v_add_f32_e32 v49, 1.0, v49
	v_rcp_f32_e32 v48, v48
	v_rcp_f32_e32 v49, v49
	s_nop 0
	v_pk_mul_f32 v[40:41], v[40:41], v[48:49]
	s_nop 0
	v_pk_mul_f32 v[40:41], v[44:45], v[40:41]
	s_nop 0
	v_cvt_pk_bf16_f32 v40, v40, v41
	v_mul_f32_e32 v41, 0xbfb8aa3b, v42
	v_exp_f32_e32 v41, v41
	s_nop 0
	v_add_f32_e32 v41, 1.0, v41
	v_rcp_f32_e32 v44, v41
	v_mul_f32_e32 v41, 0xbfb8aa3b, v43
	v_exp_f32_e32 v41, v41
	s_nop 0
	v_add_f32_e32 v41, 1.0, v41
	v_rcp_f32_e32 v45, v41
	s_nop 0
	v_pk_mul_f32 v[42:43], v[42:43], v[44:45]
	s_nop 0
	v_pk_mul_f32 v[42:43], v[46:47], v[42:43]
	s_nop 0
	v_cvt_pk_bf16_f32 v41, v42, v43
	v_add_co_u32_e32 v42, vcc, s18, v130
	s_mov_b32 s18, 0x1b8000
	s_nop 0
	v_addc_co_u32_e32 v43, vcc, 0, v131, vcc
	global_store_dwordx2 v[42:43], v[40:41], off
	v_mul_f32_e32 v40, 0xbfb8aa3b, v32
	v_mul_f32_e32 v41, 0xbfb8aa3b, v33
	v_exp_f32_e32 v40, v40
	v_exp_f32_e32 v41, v41
	v_add_f32_e32 v40, 1.0, v40
	v_add_f32_e32 v41, 1.0, v41
	v_rcp_f32_e32 v40, v40
	v_rcp_f32_e32 v41, v41
	s_nop 0
	v_pk_mul_f32 v[32:33], v[32:33], v[40:41]
	s_nop 0
	v_pk_mul_f32 v[32:33], v[36:37], v[32:33]
	s_nop 0
	v_cvt_pk_bf16_f32 v32, v32, v33
	v_mul_f32_e32 v33, 0xbfb8aa3b, v34
	v_exp_f32_e32 v33, v33
	s_nop 0
	v_add_f32_e32 v33, 1.0, v33
	v_rcp_f32_e32 v36, v33
	v_mul_f32_e32 v33, 0xbfb8aa3b, v35
	v_exp_f32_e32 v33, v33
	s_nop 0
	v_add_f32_e32 v33, 1.0, v33
	v_rcp_f32_e32 v37, v33
	s_nop 0
	v_pk_mul_f32 v[34:35], v[34:35], v[36:37]
	s_nop 0
	v_pk_mul_f32 v[34:35], v[38:39], v[34:35]
	s_nop 0
	v_cvt_pk_bf16_f32 v33, v34, v35
	global_store_dwordx2 v[42:43], v[32:33], off offset:32
	v_mul_f32_e32 v32, 0xbfb8aa3b, v24
	v_mul_f32_e32 v33, 0xbfb8aa3b, v25
	v_exp_f32_e32 v32, v32
	v_exp_f32_e32 v33, v33
	v_add_f32_e32 v32, 1.0, v32
	v_add_f32_e32 v33, 1.0, v33
	v_rcp_f32_e32 v32, v32
	v_rcp_f32_e32 v33, v33
	s_nop 0
	v_pk_mul_f32 v[24:25], v[24:25], v[32:33]
	s_nop 0
	v_pk_mul_f32 v[24:25], v[28:29], v[24:25]
	s_nop 0
	v_cvt_pk_bf16_f32 v24, v24, v25
	v_mul_f32_e32 v25, 0xbfb8aa3b, v26
	v_exp_f32_e32 v25, v25
	s_nop 0
	v_add_f32_e32 v25, 1.0, v25
	v_rcp_f32_e32 v28, v25
	v_mul_f32_e32 v25, 0xbfb8aa3b, v27
	v_exp_f32_e32 v25, v25
	s_nop 0
	v_add_f32_e32 v25, 1.0, v25
	v_rcp_f32_e32 v29, v25
	s_nop 0
	v_pk_mul_f32 v[26:27], v[26:27], v[28:29]
	s_nop 0
	v_pk_mul_f32 v[26:27], v[30:31], v[26:27]
	s_nop 0
	v_cvt_pk_bf16_f32 v25, v26, v27
	v_add_co_u32_e32 v26, vcc, s18, v130
	s_mov_b32 s18, 0x1e4000
	s_nop 0
	v_addc_co_u32_e32 v27, vcc, 0, v131, vcc
	global_store_dwordx2 v[26:27], v[24:25], off
	v_mul_f32_e32 v24, 0xbfb8aa3b, v16
	v_mul_f32_e32 v25, 0xbfb8aa3b, v17
	v_exp_f32_e32 v24, v24
	v_exp_f32_e32 v25, v25
	v_add_f32_e32 v24, 1.0, v24
	v_add_f32_e32 v25, 1.0, v25
	v_rcp_f32_e32 v24, v24
	v_rcp_f32_e32 v25, v25
	s_nop 0
	v_pk_mul_f32 v[16:17], v[16:17], v[24:25]
	s_nop 0
	v_pk_mul_f32 v[16:17], v[20:21], v[16:17]
	s_nop 0
	v_cvt_pk_bf16_f32 v16, v16, v17
	v_mul_f32_e32 v17, 0xbfb8aa3b, v18
	v_exp_f32_e32 v17, v17
	s_nop 0
	v_add_f32_e32 v17, 1.0, v17
	v_rcp_f32_e32 v20, v17
	v_mul_f32_e32 v17, 0xbfb8aa3b, v19
	v_exp_f32_e32 v17, v17
	s_nop 0
	v_add_f32_e32 v17, 1.0, v17
	v_rcp_f32_e32 v21, v17
	s_nop 0
	v_pk_mul_f32 v[18:19], v[18:19], v[20:21]
	s_nop 0
	v_pk_mul_f32 v[18:19], v[22:23], v[18:19]
	s_nop 0
	v_cvt_pk_bf16_f32 v17, v18, v19
	global_store_dwordx2 v[26:27], v[16:17], off offset:32
	v_mul_f32_e32 v16, 0xbfb8aa3b, v8
	v_mul_f32_e32 v17, 0xbfb8aa3b, v9
	v_exp_f32_e32 v16, v16
	v_exp_f32_e32 v17, v17
	v_add_f32_e32 v16, 1.0, v16
	v_add_f32_e32 v17, 1.0, v17
	v_rcp_f32_e32 v16, v16
	v_rcp_f32_e32 v17, v17
	s_nop 0
	v_pk_mul_f32 v[8:9], v[8:9], v[16:17]
	s_nop 0
	v_pk_mul_f32 v[8:9], v[12:13], v[8:9]
	s_nop 0
	v_cvt_pk_bf16_f32 v8, v8, v9
	v_mul_f32_e32 v9, 0xbfb8aa3b, v10
	v_exp_f32_e32 v9, v9
	s_nop 0
	v_add_f32_e32 v9, 1.0, v9
	v_rcp_f32_e32 v12, v9
	v_mul_f32_e32 v9, 0xbfb8aa3b, v11
	v_exp_f32_e32 v9, v9
	s_nop 0
	v_add_f32_e32 v9, 1.0, v9
	v_rcp_f32_e32 v13, v9
	s_nop 0
	v_pk_mul_f32 v[10:11], v[10:11], v[12:13]
	s_nop 0
	v_pk_mul_f32 v[10:11], v[14:15], v[10:11]
	s_nop 0
	v_cvt_pk_bf16_f32 v9, v10, v11
	v_add_co_u32_e32 v10, vcc, s18, v130
	s_mov_b32 s18, s84
	s_nop 0
	v_addc_co_u32_e32 v11, vcc, 0, v131, vcc
	global_store_dwordx2 v[10:11], v[8:9], off
	v_mul_f32_e32 v8, 0xbfb8aa3b, v0
	v_mul_f32_e32 v9, 0xbfb8aa3b, v1
	v_exp_f32_e32 v8, v8
	v_exp_f32_e32 v9, v9
	v_add_f32_e32 v8, 1.0, v8
	v_add_f32_e32 v9, 1.0, v9
	v_rcp_f32_e32 v8, v8
	v_rcp_f32_e32 v9, v9
	s_nop 0
	v_pk_mul_f32 v[0:1], v[0:1], v[8:9]
	s_nop 0
	v_pk_mul_f32 v[0:1], v[4:5], v[0:1]
	s_nop 0
	v_cvt_pk_bf16_f32 v0, v0, v1
	v_mul_f32_e32 v1, 0xbfb8aa3b, v2
	v_exp_f32_e32 v1, v1
	s_nop 0
	v_add_f32_e32 v1, 1.0, v1
	v_rcp_f32_e32 v4, v1
	v_mul_f32_e32 v1, 0xbfb8aa3b, v3
	v_exp_f32_e32 v1, v1
	s_nop 0
	v_add_f32_e32 v1, 1.0, v1
	v_rcp_f32_e32 v5, v1
	s_nop 0
	v_pk_mul_f32 v[2:3], v[2:3], v[4:5]
	s_nop 0
	v_pk_mul_f32 v[2:3], v[6:7], v[2:3]
	s_nop 0
	v_cvt_pk_bf16_f32 v1, v2, v3
	global_store_dwordx2 v[10:11], v[0:1], off offset:32
	s_barrier
	s_add_i32 s13, s18, s13
	s_cmpk_gt_i32 s13, 0x57f
	s_cbranch_scc1 .LBB0_118

; template <int EPI> ...
;     ...
;         float rs[2][4];
; #pragma unroll
;         for (int ai = 0; ai < 2; ++ai)
; #pragma unroll
;             for (int m = 0; m < 4; ++m) {
;                 const f32x4 q0 = *(const f32x4*)(ssq_in + (size_t)(row0 + ai * HALF + m * 16) * 8), q1 = *(const f32x4*)(ssq_in + (size_t)(row0 + ai * HALF + m * 16) * 8 + 4);
;                 rs[ai][m] = rsqrtf((((q0.x + q0.y) + (q0.z + q0.w)) + ((q1.x + q1.y) + (q1.z + q1.w))) * (1.f / DM) + 1e-6f);
;             }
.LBB0_790:
	s_or_b64 exec, exec, s[22:23]
	v_mov_b32_e32 v139, v224
	s_mov_b32 s22, 0x3a000000
	v_ashrrev_i32_e32 v128, 2, v139
	v_and_b32_e32 v128, 0xffffffc0, v128
	v_and_or_b32 v129, v139, 15, s20
	v_add_u32_e32 v136, v129, v128
	v_ashrrev_i32_e32 v137, 31, v136
	v_lshlrev_b64 v[128:129], 5, v[136:137]
	v_lshl_add_u64 v[128:129], s[16:17], 0, v[128:129]
	global_load_dwordx4 v[160:163], v[128:129], off
	global_load_dwordx4 v[164:167], v[128:129], off offset:16
	global_load_dwordx4 v[168:171], v[128:129], off offset:512
	global_load_dwordx4 v[172:175], v[128:129], off offset:528
	global_load_dwordx4 v[176:179], v[128:129], off offset:1024
	global_load_dwordx4 v[180:183], v[128:129], off offset:1040
	global_load_dwordx4 v[184:187], v[128:129], off offset:1536
	global_load_dwordx4 v[188:191], v[128:129], off offset:1552
	v_add_co_u32_e32 v158, vcc, 0x1000, v128
	s_nop 1
	v_addc_co_u32_e32 v159, vcc, 0, v129, vcc
	global_load_dwordx4 v[192:195], v[158:159], off
	global_load_dwordx4 v[196:199], v[158:159], off offset:16
	global_load_dwordx4 v[200:203], v[158:159], off offset:512
	global_load_dwordx4 v[204:207], v[158:159], off offset:528
	global_load_dwordx4 v[208:211], v[158:159], off offset:1024
	global_load_dwordx4 v[216:219], v[158:159], off offset:1040
	global_load_dwordx4 v[220:223], v[158:159], off offset:1536
	global_load_dwordx4 v[238:241], v[158:159], off offset:1552
	s_waitcnt vmcnt(14)
	v_mov_b32_e32 v130, v160
	v_mov_b32_e32 v131, v161
	v_mov_b32_e32 v132, v162
	v_mov_b32_e32 v133, v163
	v_mov_b32_e32 v140, v164
	v_mov_b32_e32 v141, v165
	v_mov_b32_e32 v142, v166
	v_mov_b32_e32 v143, v167
	s_mov_b64 s[20:21], 0x1000
	v_mov_b32_e32 v134, v130
	v_mov_b32_e32 v135, v140
	v_mov_b32_e32 v140, v131
	v_pk_add_f32 v[130:131], v[134:135], v[140:141]
	v_mov_b32_e32 v134, v132
	v_mov_b32_e32 v135, v142
	v_mov_b32_e32 v142, v133
	v_pk_add_f32 v[132:133], v[134:135], v[142:143]
	s_nop 0
	v_pk_add_f32 v[134:135], v[130:131], v[132:133]
	v_or_b32_e32 v130, 16, v136
	v_ashrrev_i32_e32 v131, 31, v130
	v_lshlrev_b64 v[130:131], 5, v[130:131]
	v_lshl_add_u64 v[140:141], s[16:17], 0, v[130:131]
	s_waitcnt vmcnt(12)
	v_mov_b32_e32 v130, v168
	v_mov_b32_e32 v131, v169
	v_mov_b32_e32 v132, v170
	v_mov_b32_e32 v133, v171
	s_nop 0
	v_mov_b32_e32 v140, v172
	v_mov_b32_e32 v141, v173
	v_mov_b32_e32 v142, v174
	v_mov_b32_e32 v143, v175
	v_mov_b32_e32 v144, v130
	v_mov_b32_e32 v145, v140
	v_mov_b32_e32 v140, v131
	v_pk_add_f32 v[130:131], v[144:145], v[140:141]
	v_mov_b32_e32 v140, v132
	v_mov_b32_e32 v141, v142
	v_mov_b32_e32 v142, v133
	v_pk_add_f32 v[132:133], v[140:141], v[142:143]
	v_mov_b64_e32 v[142:143], s[62:63]
	v_pk_add_f32 v[130:131], v[130:131], v[132:133]
	v_mov_b32_e32 v133, v134
	v_mov_b32_e32 v132, v130
	v_mov_b32_e32 v134, v131
	v_pk_add_f32 v[130:131], v[132:133], v[134:135]
	s_nop 0
	v_pk_fma_f32 v[130:131], v[130:131], s[22:23], v[142:143] op_sel_hi:[1,0,0]
	s_nop 0
	v_mul_f32_e32 v132, 0x4b800000, v131
	v_cmp_gt_f32_e64 s[40:41], s96, v131
	v_cmp_gt_f32_e32 vcc, s96, v130
	s_nop 0
	v_cndmask_b32_e64 v131, v131, v132, s[40:41]
	v_rsq_f32_e32 v131, v131
	s_nop 0
	v_mul_f32_e32 v132, 0x45800000, v131
	v_cndmask_b32_e64 v140, v131, v132, s[40:41]
	v_mul_f32_e32 v131, 0x4b800000, v130
	v_cndmask_b32_e32 v130, v130, v131, vcc
	v_rsq_f32_e32 v130, v130
	v_pk_mul_f32 v[114:115], v[114:115], v[140:141] op_sel_hi:[1,0]
	v_pk_mul_f32 v[112:113], v[112:113], v[140:141] op_sel_hi:[1,0]
	v_pk_mul_f32 v[118:119], v[118:119], v[140:141] op_sel_hi:[1,0]
	v_mul_f32_e32 v131, 0x45800000, v130
	v_cndmask_b32_e32 v138, v130, v131, vcc
	v_or_b32_e32 v130, 32, v136
	v_ashrrev_i32_e32 v131, 31, v130
	v_lshlrev_b64 v[130:131], 5, v[130:131]
	v_lshl_add_u64 v[134:135], s[16:17], 0, v[130:131]
	s_waitcnt vmcnt(10)
	v_mov_b32_e32 v130, v176
	v_mov_b32_e32 v131, v177
	v_mov_b32_e32 v132, v178
	v_mov_b32_e32 v133, v179
	v_mov_b32_e32 v144, v180
	v_mov_b32_e32 v145, v181
	v_mov_b32_e32 v146, v182
	v_mov_b32_e32 v147, v183
	v_pk_mul_f32 v[98:99], v[98:99], v[138:139] op_sel_hi:[1,0]
	v_pk_mul_f32 v[96:97], v[96:97], v[138:139] op_sel_hi:[1,0]
	v_pk_mul_f32 v[116:117], v[116:117], v[140:141] op_sel_hi:[1,0]
	v_pk_mul_f32 v[106:107], v[106:107], v[138:139] op_sel_hi:[1,0]
	v_pk_mul_f32 v[104:105], v[104:105], v[138:139] op_sel_hi:[1,0]
	v_mov_b32_e32 v134, v130
	v_mov_b32_e32 v135, v144
	v_mov_b32_e32 v144, v131
	v_pk_add_f32 v[130:131], v[134:135], v[144:145]
	v_mov_b32_e32 v134, v132
	v_mov_b32_e32 v135, v146
	v_mov_b32_e32 v146, v133
	v_pk_add_f32 v[132:133], v[134:135], v[146:147]
	s_nop 0
	v_pk_add_f32 v[134:135], v[130:131], v[132:133]
	v_or_b32_e32 v130, 48, v136
	v_ashrrev_i32_e32 v131, 31, v130
	v_lshlrev_b64 v[130:131], 5, v[130:131]
	v_lshl_add_u64 v[144:145], s[16:17], 0, v[130:131]
	s_waitcnt vmcnt(8)
	v_mov_b32_e32 v130, v184
	v_mov_b32_e32 v131, v185
	v_mov_b32_e32 v132, v186
	v_mov_b32_e32 v133, v187
	s_nop 0
	v_mov_b32_e32 v144, v188
	v_mov_b32_e32 v145, v189
	v_mov_b32_e32 v146, v190
	v_mov_b32_e32 v147, v191
	v_mov_b32_e32 v148, v130
	v_mov_b32_e32 v149, v144
	v_mov_b32_e32 v144, v131
	v_pk_add_f32 v[130:131], v[148:149], v[144:145]
	v_mov_b32_e32 v144, v132
	v_mov_b32_e32 v145, v146
	v_mov_b32_e32 v146, v133
	v_pk_add_f32 v[132:133], v[144:145], v[146:147]
	v_lshl_add_u64 v[148:149], v[128:129], 0, s[20:21]
	v_pk_add_f32 v[130:131], v[130:131], v[132:133]
	v_mov_b32_e32 v133, v134
	v_mov_b32_e32 v132, v130
	v_mov_b32_e32 v134, v131
	v_pk_add_f32 v[130:131], v[132:133], v[134:135]
	s_mov_b64 s[20:21], 0x1200
	v_pk_fma_f32 v[130:131], v[130:131], s[22:23], v[142:143] op_sel_hi:[1,0,0]
	s_nop 0
	v_mul_f32_e32 v132, 0x4b800000, v131
	v_cmp_gt_f32_e64 s[40:41], s96, v131
	v_cmp_gt_f32_e32 vcc, s96, v130
	s_nop 0
	v_cndmask_b32_e64 v131, v131, v132, s[40:41]
	v_rsq_f32_e32 v131, v131
	s_nop 0
	v_mul_f32_e32 v132, 0x45800000, v131
	v_cndmask_b32_e64 v146, v131, v132, s[40:41]
	v_mul_f32_e32 v131, 0x4b800000, v130
	v_cndmask_b32_e32 v130, v130, v131, vcc
	v_rsq_f32_e32 v130, v130
	v_pk_mul_f32 v[82:83], v[82:83], v[146:147] op_sel_hi:[1,0]
	v_pk_mul_f32 v[80:81], v[80:81], v[146:147] op_sel_hi:[1,0]
	v_pk_mul_f32 v[90:91], v[90:91], v[146:147] op_sel_hi:[1,0]
	v_mul_f32_e32 v131, 0x45800000, v130
	v_cndmask_b32_e32 v144, v130, v131, vcc
	v_add_co_u32_e32 v130, vcc, s70, v128
	v_pk_mul_f32 v[50:51], v[50:51], v[144:145] op_sel_hi:[1,0]
	s_nop 0
	v_addc_co_u32_e32 v131, vcc, 0, v129, vcc
	s_waitcnt vmcnt(6)
; __device__ __forceinline__ unsigned pk2(float lo, float hi) { f32x2_t v = {lo, hi}; bf16x2_t b = __builtin_convertvector(v, bf16x2_t); return __builtin_bit_cast(unsigned, b); }
; __device__ __forceinline__ float siluf_(float x) { return x * __builtin_amdgcn_rcpf(1.f + __expf(-x)); }
; template <int EPI> ...
;     ...
;                 const f32x4 q0 = *(const f32x4*)(ssq_in + (size_t)(row0 + ai * HALF + m * 16) * 8), q1 = *(const f32x4*)(ssq_in + (size_t)(row0 + ai * HALF + m * 16) * 8 + 4);
;                 rs[ai][m] = rsqrtf((((q0.x + q0.y) + (q0.z + q0.w)) + ((q1.x + q1.y) + (q1.z + q1.w))) * (1.f / DM) + 1e-6f);
;             }
;         if (EPI == EPI_SWIGLU) {
;             bf16_t* base = Cb + (size_t)row0 * ldc + (bcol >> 1) + wc * 32 + 4 * fq;
; #pragma unroll
;             for (int ai = 0; ai < 2; ++ai)
; #pragma unroll
;                 for (int m = 0; m < 4; ++m)
; #pragma unroll
;                     for (int n = 0; n < 2; ++n) {
;                         const f32x4 g = acc[ai][0][m][n] * rs[ai][m], u = acc[ai][1][m][n] * rs[ai][m];
;                         u32x2 o; o.x = pk2(siluf_(g.x) * u.x, siluf_(g.y) * u.y); o.y = pk2(siluf_(g.z) * u.z, siluf_(g.w) * u.w);
;                         *(u32x2*)(base + (size_t)(ai * HALF + m * 16) * ldc + n * 16) = o;
;                     }
;         } else {
;             float* base = Cf + (size_t)row0 * ldc + bcol + wc * 32 + 4 * fq;
; #pragma unroll
;             for (int ai = 0; ai < 2; ++ai)
; #pragma unroll
;                 for (int m = 0; m < 4; ++m)
; #pragma unroll
;                     for (int bj = 0; bj < 2; ++bj)
; #pragma unroll
;                         for (int n = 0; n < 2; ++n) *(f32x4*)(base + (size_t)(ai * HALF + m * 16) * ldc + bj * HALF + n * 16) = acc[ai][bj][m][n] * rs[ai][m];
	v_mov_b32_e32 v132, v192
	v_mov_b32_e32 v133, v193
	v_mov_b32_e32 v134, v194
	v_mov_b32_e32 v135, v195
	s_nop 0
	v_mov_b32_e32 v148, v196
	v_mov_b32_e32 v149, v197
	v_mov_b32_e32 v150, v198
	v_mov_b32_e32 v151, v199
	v_pk_mul_f32 v[48:49], v[48:49], v[144:145] op_sel_hi:[1,0]
	v_pk_mul_f32 v[88:89], v[88:89], v[146:147] op_sel_hi:[1,0]
	v_pk_mul_f32 v[70:71], v[70:71], v[144:145] op_sel_hi:[1,0]
	v_pk_mul_f32 v[68:69], v[68:69], v[144:145] op_sel_hi:[1,0]
	v_mov_b32_e32 v152, v132
	v_mov_b32_e32 v153, v148
	v_mov_b32_e32 v148, v133
	v_pk_add_f32 v[132:133], v[152:153], v[148:149]
	v_mov_b32_e32 v148, v134
	v_mov_b32_e32 v149, v150
	v_mov_b32_e32 v150, v135
	v_pk_add_f32 v[134:135], v[148:149], v[150:151]
	v_lshl_add_u64 v[148:149], v[128:129], 0, s[20:21]
	v_pk_add_f32 v[152:153], v[132:133], v[134:135]
	s_waitcnt vmcnt(4)
	v_mov_b32_e32 v132, v200
	v_mov_b32_e32 v133, v201
	v_mov_b32_e32 v134, v202
	v_mov_b32_e32 v135, v203
	s_nop 0
	v_mov_b32_e32 v148, v204
	v_mov_b32_e32 v149, v205
	v_mov_b32_e32 v150, v206
	v_mov_b32_e32 v151, v207
	s_mov_b64 s[20:21], 0x1400
	v_mov_b32_e32 v154, v132
	v_mov_b32_e32 v155, v148
	v_mov_b32_e32 v148, v133
	v_pk_add_f32 v[132:133], v[154:155], v[148:149]
	v_mov_b32_e32 v148, v134
	v_mov_b32_e32 v149, v150
	v_mov_b32_e32 v150, v135
	v_pk_add_f32 v[134:135], v[148:149], v[150:151]
	s_nop 0
	v_pk_add_f32 v[132:133], v[132:133], v[134:135]
	v_mov_b32_e32 v135, v152
	v_mov_b32_e32 v134, v132
	v_mov_b32_e32 v152, v133
	v_pk_add_f32 v[132:133], v[134:135], v[152:153]
	v_lshl_add_u64 v[152:153], v[128:129], 0, s[20:21]
	v_pk_fma_f32 v[132:133], v[132:133], s[22:23], v[142:143] op_sel_hi:[1,0,0]
	s_mov_b64 s[20:21], 0x1600
	v_mul_f32_e32 v134, 0x4b800000, v133
	v_cmp_gt_f32_e64 s[40:41], s96, v133
	v_cmp_gt_f32_e32 vcc, s96, v132
	s_nop 0
	v_cndmask_b32_e64 v133, v133, v134, s[40:41]
	v_rsq_f32_e32 v133, v133
	s_nop 0
	v_mul_f32_e32 v134, 0x45800000, v133
	v_cndmask_b32_e64 v150, v133, v134, s[40:41]
	v_mul_f32_e32 v133, 0x4b800000, v132
	v_cndmask_b32_e32 v132, v132, v133, vcc
	v_rsq_f32_e32 v132, v132
	s_nop 0
	v_mul_f32_e32 v133, 0x45800000, v132
	v_cndmask_b32_e32 v148, v132, v133, vcc
	s_waitcnt vmcnt(2)
	v_mov_b32_e32 v132, v208
	v_mov_b32_e32 v133, v209
	v_mov_b32_e32 v134, v210
	v_mov_b32_e32 v135, v211
	s_nop 0
	v_mov_b32_e32 v152, v216
	v_mov_b32_e32 v153, v217
	v_mov_b32_e32 v154, v218
	v_mov_b32_e32 v155, v219
	v_pk_mul_f32 v[34:35], v[34:35], v[148:149] op_sel_hi:[1,0]
	v_pk_mul_f32 v[32:33], v[32:33], v[148:149] op_sel_hi:[1,0]
	v_pk_mul_f32 v[46:47], v[46:47], v[148:149] op_sel_hi:[1,0]
	v_pk_mul_f32 v[44:45], v[44:45], v[148:149] op_sel_hi:[1,0]
	v_mov_b32_e32 v156, v132
	v_mov_b32_e32 v157, v152
	v_mov_b32_e32 v152, v133
	v_pk_add_f32 v[132:133], v[156:157], v[152:153]
	v_mov_b32_e32 v152, v134
	v_mov_b32_e32 v153, v154
	v_mov_b32_e32 v154, v135
	v_pk_add_f32 v[134:135], v[152:153], v[154:155]
	s_nop 0
	v_pk_add_f32 v[152:153], v[132:133], v[134:135]
	v_lshl_add_u64 v[132:133], v[128:129], 0, s[20:21]
	s_waitcnt vmcnt(0)
	v_mov_b32_e32 v128, v220
	v_mov_b32_e32 v129, v221
	v_mov_b32_e32 v130, v222
	v_mov_b32_e32 v131, v223
	s_nop 0
	v_mov_b32_e32 v132, v238
	v_mov_b32_e32 v133, v239
	v_mov_b32_e32 v134, v240
	v_mov_b32_e32 v135, v241
	v_mov_b32_e32 v154, v128
	v_mov_b32_e32 v155, v132
	v_mov_b32_e32 v132, v129
	v_pk_add_f32 v[128:129], v[154:155], v[132:133]
	v_mov_b32_e32 v132, v130
	v_mov_b32_e32 v133, v134
	v_mov_b32_e32 v134, v131
	v_pk_add_f32 v[130:131], v[132:133], v[134:135]
	v_mov_b64_e32 v[132:133], s[2:3]
	v_pk_add_f32 v[128:129], v[128:129], v[130:131]
	v_mov_b32_e32 v131, v152
	v_mov_b32_e32 v130, v128
	v_mov_b32_e32 v152, v129
	v_pk_add_f32 v[128:129], v[130:131], v[152:153]
	v_mad_i64_i32 v[132:133], s[20:21], v136, s95, v[132:133]
	v_pk_fma_f32 v[128:129], v[128:129], s[22:23], v[142:143] op_sel_hi:[1,0,0]
	v_lshl_add_u64 v[132:133], s[18:19], 2, v[132:133]
	v_mul_f32_e32 v130, 0x4b800000, v129
	v_cmp_gt_f32_e64 s[40:41], s96, v129
	v_cmp_gt_f32_e32 vcc, s96, v128
	s_mov_b32 s18, 0x78000
	v_cndmask_b32_e64 v129, v129, v130, s[40:41]
	v_rsq_f32_e32 v129, v129
	s_nop 0
	v_mul_f32_e32 v130, 0x45800000, v129
	v_cndmask_b32_e64 v130, v129, v130, s[40:41]
	v_mul_f32_e32 v129, 0x4b800000, v128
	v_cndmask_b32_e32 v128, v128, v129, vcc
	v_rsq_f32_e32 v128, v128
	v_pk_mul_f32 v[18:19], v[18:19], v[130:131] op_sel_hi:[1,0]
	v_pk_mul_f32 v[16:17], v[16:17], v[130:131] op_sel_hi:[1,0]
	v_pk_mul_f32 v[30:31], v[30:31], v[130:131] op_sel_hi:[1,0]
	v_mul_f32_e32 v129, 0x45800000, v128
	v_cndmask_b32_e32 v128, v128, v129, vcc
	v_lshlrev_b32_e32 v129, 1, v139
	v_and_b32_e32 v214, 0x180, v129
	v_lshl_add_u64 v[132:133], v[132:133], 0, v[214:215]
	v_and_b32_e32 v214, 48, v139
	v_lshl_add_u64 v[132:133], v[132:133], 0, v[214:215]
	global_store_dwordx4 v[132:133], v[112:115], off offset:64 nt
	v_pk_mul_f32 v[2:3], v[2:3], v[128:129] op_sel_hi:[1,0]
	v_pk_mul_f32 v[0:1], v[0:1], v[128:129] op_sel_hi:[1,0]
	v_pk_mul_f32 v[114:115], v[126:127], v[140:141] op_sel_hi:[1,0]
	v_pk_mul_f32 v[112:113], v[124:125], v[140:141] op_sel_hi:[1,0]
; #define BIDX opaque_bid()
; #define GDIM opaque_gdim()
; template <int EPI> ...
;     ...
;             float* base = Cf + (size_t)row0 * ldc + bcol + wc * 32 + 4 * fq;
; #pragma unroll
;             for (int ai = 0; ai < 2; ++ai)
; #pragma unroll
;                 for (int m = 0; m < 4; ++m)
; #pragma unroll
;                     for (int bj = 0; bj < 2; ++bj)
; #pragma unroll
;                         for (int n = 0; n < 2; ++n) *(f32x4*)(base + (size_t)(ai * HALF + m * 16) * ldc + bj * HALF + n * 16) = acc[ai][bj][m][n] * rs[ai][m];
; template <int EPI>
; __device__ __forceinline__ void gemm_phase(const bf16_t* A, const bf16_t* Bt, int M, int N, int K, bf16_t* shm,
;                                            float* Cf, bf16_t* Cb, int ldc, float scale, const float* gvec, bf16_t* XNout, float* ssq_out, const float* ssq_in) {
;     ...
;     for (int L = BIDX; L < nwg; L += GDIM) {
;         int wgid = L;
;         { int q = nwg / NXCD, r = nwg % NXCD, xcd = wgid % NXCD, off = wgid / NXCD;
;           wgid = (xcd < r ? xcd * (q + 1) : r * (q + 1) + (xcd - r) * q) + off; }
;         int nig = WGM * nN, gid = wgid / nig, fm = gid * WGM, gsz = min(nM - fm, WGM);
;         int pm = fm + ((wgid % nig) % gsz), pn = (wgid % nig) / gsz;
;         gemm_unit<EPI>(A, Bt, K, pm * BM, pn * BM, shm, Cf, Cb, ldc, scale, gvec, XNout, ssq_out, ssq_in);
;     }
	global_store_dwordx4 v[132:133], v[112:115], off offset:512 nt
	v_pk_mul_f32 v[28:29], v[28:29], v[130:131] op_sel_hi:[1,0]
	v_pk_mul_f32 v[14:15], v[14:15], v[128:129] op_sel_hi:[1,0]
	v_pk_mul_f32 v[114:115], v[122:123], v[140:141] op_sel_hi:[1,0]
	v_pk_mul_f32 v[112:113], v[120:121], v[140:141] op_sel_hi:[1,0]
	global_store_dwordx4 v[132:133], v[112:115], off offset:576 nt
	v_pk_mul_f32 v[12:13], v[12:13], v[128:129] op_sel_hi:[1,0]
	global_store_dwordx4 v[132:133], v[116:119], off nt
	v_add_co_u32_e32 v112, vcc, s18, v132
	s_mov_b32 s18, 0xf0000
	s_nop 0
	v_addc_co_u32_e32 v113, vcc, 0, v133, vcc
	global_store_dwordx4 v[112:113], v[96:99], off offset:64 nt
	global_store_dwordx4 v[112:113], v[104:107], off nt
	s_nop 0
	v_pk_mul_f32 v[98:99], v[110:111], v[138:139] op_sel_hi:[1,0]
	v_pk_mul_f32 v[96:97], v[108:109], v[138:139] op_sel_hi:[1,0]
	global_store_dwordx4 v[112:113], v[96:99], off offset:512 nt
	s_nop 1
	v_pk_mul_f32 v[98:99], v[102:103], v[138:139] op_sel_hi:[1,0]
	v_pk_mul_f32 v[96:97], v[100:101], v[138:139] op_sel_hi:[1,0]
	global_store_dwordx4 v[112:113], v[96:99], off offset:576 nt
	s_nop 1
	v_add_co_u32_e32 v96, vcc, s18, v132
	s_mov_b32 s18, 0x168000
	s_nop 0
	v_addc_co_u32_e32 v97, vcc, 0, v133, vcc
	global_store_dwordx4 v[96:97], v[80:83], off offset:64 nt
	global_store_dwordx4 v[96:97], v[88:91], off nt
	s_nop 0
	v_pk_mul_f32 v[82:83], v[94:95], v[146:147] op_sel_hi:[1,0]
	v_pk_mul_f32 v[80:81], v[92:93], v[146:147] op_sel_hi:[1,0]
	global_store_dwordx4 v[96:97], v[80:83], off offset:512 nt
	s_nop 1
	v_pk_mul_f32 v[82:83], v[86:87], v[146:147] op_sel_hi:[1,0]
	v_pk_mul_f32 v[80:81], v[84:85], v[146:147] op_sel_hi:[1,0]
	global_store_dwordx4 v[96:97], v[80:83], off offset:576 nt
	s_nop 1
	v_add_co_u32_e32 v80, vcc, s18, v132
	s_mov_b32 s18, 0x3c0000
	s_nop 0
	v_addc_co_u32_e32 v81, vcc, 0, v133, vcc
	global_store_dwordx4 v[80:81], v[48:51], off offset:64 nt
	global_store_dwordx4 v[80:81], v[68:71], off nt
	s_nop 0
	v_pk_mul_f32 v[50:51], v[78:79], v[144:145] op_sel_hi:[1,0]
	v_pk_mul_f32 v[48:49], v[76:77], v[144:145] op_sel_hi:[1,0]
	global_store_dwordx4 v[80:81], v[48:51], off offset:512 nt
	s_nop 1
	v_pk_mul_f32 v[50:51], v[62:63], v[144:145] op_sel_hi:[1,0]
	v_pk_mul_f32 v[48:49], v[60:61], v[144:145] op_sel_hi:[1,0]
	v_add_co_u32_e32 v60, vcc, s18, v132
	global_store_dwordx4 v[80:81], v[48:51], off offset:576 nt
	s_nop 0
	v_addc_co_u32_e32 v61, vcc, 0, v133, vcc
	v_pk_mul_f32 v[50:51], v[74:75], v[150:151] op_sel_hi:[1,0]
	v_pk_mul_f32 v[48:49], v[72:73], v[150:151] op_sel_hi:[1,0]
	global_store_dwordx4 v[60:61], v[48:51], off nt
	s_mov_b32 s18, 0x438000
	s_nop 0
	v_pk_mul_f32 v[50:51], v[54:55], v[150:151] op_sel_hi:[1,0]
	v_pk_mul_f32 v[48:49], v[52:53], v[150:151] op_sel_hi:[1,0]
	global_store_dwordx4 v[60:61], v[48:51], off offset:64 nt
	s_nop 1
	v_pk_mul_f32 v[50:51], v[66:67], v[150:151] op_sel_hi:[1,0]
	v_pk_mul_f32 v[48:49], v[64:65], v[150:151] op_sel_hi:[1,0]
	global_store_dwordx4 v[60:61], v[48:51], off offset:512 nt
	s_nop 1
	v_pk_mul_f32 v[50:51], v[58:59], v[150:151] op_sel_hi:[1,0]
	v_pk_mul_f32 v[48:49], v[56:57], v[150:151] op_sel_hi:[1,0]
	global_store_dwordx4 v[60:61], v[48:51], off offset:576 nt
	s_nop 1
	v_add_co_u32_e32 v48, vcc, s18, v132
	s_mov_b32 s18, 0x4b0000
	s_nop 0
	v_addc_co_u32_e32 v49, vcc, 0, v133, vcc
	global_store_dwordx4 v[48:49], v[32:35], off offset:64 nt
	global_store_dwordx4 v[48:49], v[44:47], off nt
	s_nop 0
	v_pk_mul_f32 v[34:35], v[42:43], v[148:149] op_sel_hi:[1,0]
	v_pk_mul_f32 v[32:33], v[40:41], v[148:149] op_sel_hi:[1,0]
	global_store_dwordx4 v[48:49], v[32:35], off offset:512 nt
	s_nop 1
	v_pk_mul_f32 v[34:35], v[38:39], v[148:149] op_sel_hi:[1,0]
	v_pk_mul_f32 v[32:33], v[36:37], v[148:149] op_sel_hi:[1,0]
	global_store_dwordx4 v[48:49], v[32:35], off offset:576 nt
	s_nop 1
	v_add_co_u32_e32 v32, vcc, s18, v132
	s_mov_b32 s18, 0x528000
	s_nop 0
	v_addc_co_u32_e32 v33, vcc, 0, v133, vcc
	global_store_dwordx4 v[32:33], v[16:19], off offset:64 nt
	global_store_dwordx4 v[32:33], v[28:31], off nt
	s_nop 0
	v_pk_mul_f32 v[18:19], v[26:27], v[130:131] op_sel_hi:[1,0]
	v_pk_mul_f32 v[16:17], v[24:25], v[130:131] op_sel_hi:[1,0]
	global_store_dwordx4 v[32:33], v[16:19], off offset:512 nt
	s_nop 1
	v_pk_mul_f32 v[18:19], v[22:23], v[130:131] op_sel_hi:[1,0]
	v_pk_mul_f32 v[16:17], v[20:21], v[130:131] op_sel_hi:[1,0]
	global_store_dwordx4 v[32:33], v[16:19], off offset:576 nt
	s_nop 1
	v_add_co_u32_e32 v16, vcc, s18, v132
	s_mov_b32 s18, s84
	s_nop 0
	v_addc_co_u32_e32 v17, vcc, 0, v133, vcc
	global_store_dwordx4 v[16:17], v[0:3], off offset:64 nt
	global_store_dwordx4 v[16:17], v[12:15], off nt
	s_nop 0
	v_pk_mul_f32 v[2:3], v[10:11], v[128:129] op_sel_hi:[1,0]
	v_pk_mul_f32 v[0:1], v[8:9], v[128:129] op_sel_hi:[1,0]
	global_store_dwordx4 v[16:17], v[0:3], off offset:512 nt
	s_nop 1
	v_pk_mul_f32 v[2:3], v[6:7], v[128:129] op_sel_hi:[1,0]
	v_pk_mul_f32 v[0:1], v[4:5], v[128:129] op_sel_hi:[1,0]
	global_store_dwordx4 v[16:17], v[0:3], off offset:576 nt
	s_barrier
	s_add_i32 s13, s18, s13
	s_cmpk_gt_i32 s13, 0x3bf
	s_cbranch_scc1 .LBB0_797
